# P5 out-projection epilogue: counted vmcnt waits per residual-row load of the first batch instead of one vmcnt(0) (on top of v73)
# baseline (speedup 1.0000x reference)
; __device__ __forceinline__ unsigned cvt_pk_bf16_v(float lo, float hi) { const f32x2c v = {lo, hi}; const bf16x2c b = __builtin_convertvector(v, bf16x2c); return __builtin_bit_cast(unsigned, b); }
;     __device__ __forceinline__ void operator()(const f32x4 (&acc)[2][2][4][2], const Unit& u_, int wr, int wc, int fr, int fq) const {
;     ...
;                     for (int t = 0; t < 2; ++t) xr[m][bj][t] = *(const f32x4*)(xp + (size_t)(rowb + ai * HALF + m * 16 + 8 * t) * 1024 + colb + bj * HALF);
;             asm volatile("" ::: "memory");
; #pragma unroll
;             for (int m = 0; m < 4; ++m)
; #pragma unroll
;                 for (int bj = 0; bj < 2; ++bj) { f32x4 o[2]; xchg_f32(xl, fr, fq, l, acc[ai][bj][m][0], acc[ai][bj][m][1], o[0], o[1]);
; #pragma unroll
;                     for (int t = 0; t < 2; ++t) { const f32x4 v = o[t] + xr[m][bj][t]; u32x2 w; w.x = cvt_pk_bf16_v(v[0], v[1]); w.y = cvt_pk_bf16_v(v[2], v[3]);
;                         *(u32x2*)(h1b + (size_t)(rowb + ai * HALF + m * 16 + 8 * t) * 1024 + colb + bj * HALF) = w; } }
.LBB0_836:
	s_mov_b64 s[56:57], -1
	v_lshl_add_u32 v206, s8, 8, v233
	v_lshl_or_b32 v222, s9, 8, v234
	v_ashrrev_i32_e32 v223, 31, v222
	v_ashrrev_i32_e32 v207, 31, v206
	v_lshl_add_u64 v[204:205], v[222:223], 2, s[68:69]
	v_lshlrev_b64 v[130:131], 12, v[206:207]
	v_or_b32_e32 v220, 8, v206
	v_lshl_add_u64 v[130:131], v[204:205], 0, v[130:131]
	v_ashrrev_i32_e32 v221, 31, v220
	global_load_dwordx4 v[238:241], v[130:131], off
	v_lshlrev_b64 v[132:133], 12, v[220:221]
	v_lshl_add_u64 v[132:133], v[204:205], 0, v[132:133]
	global_load_dwordx4 v[242:245], v[132:133], off
	global_load_dwordx4 v[178:181], v[130:131], off offset:512
	global_load_dwordx4 v[182:185], v[132:133], off offset:512
	v_or_b32_e32 v218, 16, v206
	v_ashrrev_i32_e32 v219, 31, v218
	v_lshlrev_b64 v[130:131], 12, v[218:219]
	v_lshl_add_u64 v[130:131], v[204:205], 0, v[130:131]
	global_load_dwordx4 v[174:177], v[130:131], off
	v_or_b32_e32 v216, 24, v206
	v_ashrrev_i32_e32 v217, 31, v216
	v_lshlrev_b64 v[132:133], 12, v[216:217]
	v_lshl_add_u64 v[132:133], v[204:205], 0, v[132:133]
	global_load_dwordx4 v[170:173], v[132:133], off
	global_load_dwordx4 v[166:169], v[130:131], off offset:512
	global_load_dwordx4 v[162:165], v[132:133], off offset:512
	v_or_b32_e32 v212, 32, v206
	v_ashrrev_i32_e32 v213, 31, v212
	v_lshlrev_b64 v[130:131], 12, v[212:213]
	v_lshl_add_u64 v[130:131], v[204:205], 0, v[130:131]
	global_load_dwordx4 v[154:157], v[130:131], off
	v_or_b32_e32 v214, 40, v206
	v_ashrrev_i32_e32 v215, 31, v214
	v_lshlrev_b64 v[132:133], 12, v[214:215]
	v_lshl_add_u64 v[132:133], v[204:205], 0, v[132:133]
	global_load_dwordx4 v[158:161], v[132:133], off
	global_load_dwordx4 v[146:149], v[130:131], off offset:512
	global_load_dwordx4 v[142:145], v[132:133], off offset:512
	v_or_b32_e32 v208, 48, v206
	v_ashrrev_i32_e32 v209, 31, v208
	v_lshlrev_b64 v[130:131], 12, v[208:209]
	v_lshl_add_u64 v[130:131], v[204:205], 0, v[130:131]
	global_load_dwordx4 v[138:141], v[130:131], off
	v_or_b32_e32 v210, 56, v206
	v_ashrrev_i32_e32 v211, 31, v210
	v_lshlrev_b64 v[132:133], 12, v[210:211]
	v_lshl_add_u64 v[132:133], v[204:205], 0, v[132:133]
	global_load_dwordx4 v[150:153], v[132:133], off
	global_load_dwordx4 v[134:137], v[130:131], off offset:512
	s_nop 0
	global_load_dwordx4 v[130:133], v[132:133], off offset:512
	ds_write_b128 v236, v[126:129]
	ds_write_b128 v236, v[122:125] offset:16
	ds_read_b128 v[122:125], v237
	ds_read_b128 v[126:129], v237 offset:1152
	s_cmp_eq_u32 s74, s72
	s_waitcnt vmcnt(14) lgkmcnt(0)
	v_pk_add_f32 v[122:123], v[238:239], v[122:123]
	v_pk_add_f32 v[128:129], v[244:245], v[128:129]
	v_pk_add_f32 v[126:127], v[242:243], v[126:127]
	v_pk_add_f32 v[124:125], v[240:241], v[124:125]
	v_cvt_pk_bf16_f32 v238, v122, v123
	v_lshlrev_b64 v[122:123], 11, v[206:207]
	v_cvt_pk_bf16_f32 v126, v126, v127
	v_cvt_pk_bf16_f32 v127, v128, v129
	v_lshlrev_b64 v[128:129], 11, v[220:221]
	v_cvt_pk_bf16_f32 v239, v124, v125
	v_lshl_add_u64 v[124:125], s[14:15], 0, v[122:123]
	v_lshlrev_b64 v[122:123], 1, v[222:223]
	v_lshl_add_u64 v[128:129], s[14:15], 0, v[128:129]
	v_lshl_add_u64 v[124:125], v[124:125], 0, v[122:123]
	v_lshl_add_u64 v[128:129], v[128:129], 0, v[122:123]
	global_store_dwordx2 v[124:125], v[238:239], off
	global_store_dwordx2 v[128:129], v[126:127], off
	ds_write_b128 v236, v[118:121]
	ds_write_b128 v236, v[114:117] offset:16
	ds_read_b128 v[114:117], v237
	ds_read_b128 v[118:121], v237 offset:1152
	s_waitcnt vmcnt(15) lgkmcnt(1)
	v_pk_add_f32 v[116:117], v[180:181], v[116:117]
	v_pk_add_f32 v[114:115], v[178:179], v[114:115]
	s_nop 0
	v_cvt_pk_bf16_f32 v114, v114, v115
	v_cvt_pk_bf16_f32 v115, v116, v117
	global_store_dwordx2 v[124:125], v[114:115], off offset:256
	s_waitcnt vmcnt(15) lgkmcnt(0)
	v_pk_add_f32 v[114:115], v[184:185], v[120:121]
	v_pk_add_f32 v[116:117], v[182:183], v[118:119]
	s_nop 0
	v_cvt_pk_bf16_f32 v116, v116, v117
	v_cvt_pk_bf16_f32 v117, v114, v115
	global_store_dwordx2 v[128:129], v[116:117], off offset:256
	ds_write_b128 v236, v[110:113]
	ds_write_b128 v236, v[106:109] offset:16
	ds_read_b128 v[106:109], v237
	ds_read_b128 v[110:113], v237 offset:1152
	s_waitcnt vmcnt(15) lgkmcnt(1)
	v_pk_add_f32 v[108:109], v[176:177], v[108:109]
	v_pk_add_f32 v[106:107], v[174:175], v[106:107]
	s_waitcnt vmcnt(14) lgkmcnt(0)
	v_pk_add_f32 v[110:111], v[170:171], v[110:111]
	v_cvt_pk_bf16_f32 v106, v106, v107
	v_cvt_pk_bf16_f32 v107, v108, v109
	v_lshlrev_b64 v[108:109], 11, v[218:219]
	v_lshl_add_u64 v[108:109], s[14:15], 0, v[108:109]
	v_lshl_add_u64 v[108:109], v[108:109], 0, v[122:123]
	global_store_dwordx2 v[108:109], v[106:107], off
	v_pk_add_f32 v[106:107], v[172:173], v[112:113]
	v_cvt_pk_bf16_f32 v110, v110, v111
	v_cvt_pk_bf16_f32 v111, v106, v107
	v_lshlrev_b64 v[106:107], 11, v[216:217]
	v_lshl_add_u64 v[106:107], s[14:15], 0, v[106:107]
	v_lshl_add_u64 v[106:107], v[106:107], 0, v[122:123]
	global_store_dwordx2 v[106:107], v[110:111], off
	ds_write_b128 v236, v[102:105]
	ds_write_b128 v236, v[98:101] offset:16
	ds_read_b128 v[98:101], v237
	ds_read_b128 v[102:105], v237 offset:1152
	s_waitcnt vmcnt(15) lgkmcnt(1)
	v_pk_add_f32 v[100:101], v[168:169], v[100:101]
	v_pk_add_f32 v[98:99], v[166:167], v[98:99]
	s_nop 0
	v_cvt_pk_bf16_f32 v98, v98, v99
	v_cvt_pk_bf16_f32 v99, v100, v101
	global_store_dwordx2 v[108:109], v[98:99], off offset:256
	s_waitcnt vmcnt(15) lgkmcnt(0)
	v_pk_add_f32 v[98:99], v[164:165], v[104:105]
	v_pk_add_f32 v[100:101], v[162:163], v[102:103]
	v_add_u32_e32 v104, 0xa0, v206
	v_cvt_pk_bf16_f32 v100, v100, v101
	v_cvt_pk_bf16_f32 v101, v98, v99
	global_store_dwordx2 v[106:107], v[100:101], off offset:256
	ds_write_b128 v236, v[94:97]
	ds_write_b128 v236, v[90:93] offset:16
	ds_read_b128 v[90:93], v237
	ds_read_b128 v[94:97], v237 offset:1152
	v_ashrrev_i32_e32 v105, 31, v104
	v_add_u32_e32 v102, 0xa8, v206
	v_ashrrev_i32_e32 v103, 31, v102
	s_waitcnt vmcnt(15) lgkmcnt(1)
; __device__ __forceinline__ unsigned cvt_pk_bf16_v(float lo, float hi) { const f32x2c v = {lo, hi}; const bf16x2c b = __builtin_convertvector(v, bf16x2c); return __builtin_bit_cast(unsigned, b); }
;     __device__ __forceinline__ void operator()(const f32x4 (&acc)[2][2][4][2], const Unit& u_, int wr, int wc, int fr, int fq) const {
;     ...
;                     for (int t = 0; t < 2; ++t) xr[m][bj][t] = *(const f32x4*)(xp + (size_t)(rowb + ai * HALF + m * 16 + 8 * t) * 1024 + colb + bj * HALF);
;             asm volatile("" ::: "memory");
; #pragma unroll
;             for (int m = 0; m < 4; ++m)
; #pragma unroll
;                 for (int bj = 0; bj < 2; ++bj) { f32x4 o[2]; xchg_f32(xl, fr, fq, l, acc[ai][bj][m][0], acc[ai][bj][m][1], o[0], o[1]);
; #pragma unroll
;                     for (int t = 0; t < 2; ++t) { const f32x4 v = o[t] + xr[m][bj][t]; u32x2 w; w.x = cvt_pk_bf16_v(v[0], v[1]); w.y = cvt_pk_bf16_v(v[2], v[3]);
;                         *(u32x2*)(h1b + (size_t)(rowb + ai * HALF + m * 16 + 8 * t) * 1024 + colb + bj * HALF) = w; } }
	v_pk_add_f32 v[92:93], v[156:157], v[92:93]
	v_pk_add_f32 v[90:91], v[154:155], v[90:91]
	s_waitcnt vmcnt(14) lgkmcnt(0)
	v_pk_add_f32 v[94:95], v[158:159], v[94:95]
	v_cvt_pk_bf16_f32 v90, v90, v91
	v_cvt_pk_bf16_f32 v91, v92, v93
	v_lshlrev_b64 v[92:93], 11, v[212:213]
	v_lshl_add_u64 v[92:93], s[14:15], 0, v[92:93]
	v_lshl_add_u64 v[92:93], v[92:93], 0, v[122:123]
	global_store_dwordx2 v[92:93], v[90:91], off
	v_pk_add_f32 v[90:91], v[160:161], v[96:97]
	v_cvt_pk_bf16_f32 v94, v94, v95
	v_cvt_pk_bf16_f32 v95, v90, v91
	v_lshlrev_b64 v[90:91], 11, v[214:215]
	v_lshl_add_u64 v[90:91], s[14:15], 0, v[90:91]
	v_lshl_add_u64 v[90:91], v[90:91], 0, v[122:123]
	global_store_dwordx2 v[90:91], v[94:95], off
	ds_write_b128 v236, v[86:89]
	ds_write_b128 v236, v[82:85] offset:16
	ds_read_b128 v[82:85], v237
	ds_read_b128 v[86:89], v237 offset:1152
	v_add_u32_e32 v100, 0xb0, v206
	v_ashrrev_i32_e32 v101, 31, v100
	v_add_u32_e32 v98, 0xb8, v206
	s_waitcnt vmcnt(15) lgkmcnt(1)
	v_pk_add_f32 v[84:85], v[148:149], v[84:85]
	v_pk_add_f32 v[82:83], v[146:147], v[82:83]
	v_add_u32_e32 v146, 0x98, v206
	v_cvt_pk_bf16_f32 v82, v82, v83
	v_cvt_pk_bf16_f32 v83, v84, v85
	global_store_dwordx2 v[92:93], v[82:83], off offset:256
	s_waitcnt vmcnt(15) lgkmcnt(0)
	v_pk_add_f32 v[82:83], v[144:145], v[88:89]
	v_pk_add_f32 v[84:85], v[142:143], v[86:87]
	v_add_u32_e32 v142, 0x88, v206
	v_cvt_pk_bf16_f32 v84, v84, v85
	v_cvt_pk_bf16_f32 v85, v82, v83
	global_store_dwordx2 v[90:91], v[84:85], off offset:256
	ds_write_b128 v236, v[78:81]
	ds_write_b128 v236, v[74:77] offset:16
	ds_read_b128 v[74:77], v237
	ds_read_b128 v[78:81], v237 offset:1152
	v_ashrrev_i32_e32 v143, 31, v142
	v_add_u32_e32 v144, 0x90, v206
	v_ashrrev_i32_e32 v145, 31, v144
	s_waitcnt vmcnt(15) lgkmcnt(1)
	v_pk_add_f32 v[76:77], v[140:141], v[76:77]
	v_pk_add_f32 v[74:75], v[138:139], v[74:75]
	s_waitcnt vmcnt(14) lgkmcnt(0)
	v_pk_add_f32 v[78:79], v[150:151], v[78:79]
	v_cvt_pk_bf16_f32 v74, v74, v75
	v_cvt_pk_bf16_f32 v75, v76, v77
	v_lshlrev_b64 v[76:77], 11, v[208:209]
	v_lshl_add_u64 v[76:77], s[14:15], 0, v[76:77]
	v_lshl_add_u64 v[76:77], v[76:77], 0, v[122:123]
	global_store_dwordx2 v[76:77], v[74:75], off
	v_pk_add_f32 v[74:75], v[152:153], v[80:81]
	v_cvt_pk_bf16_f32 v78, v78, v79
	v_cvt_pk_bf16_f32 v79, v74, v75
	v_lshlrev_b64 v[74:75], 11, v[210:211]
	v_lshl_add_u64 v[74:75], s[14:15], 0, v[74:75]
	v_lshl_add_u64 v[74:75], v[74:75], 0, v[122:123]
	global_store_dwordx2 v[74:75], v[78:79], off
	ds_write_b128 v236, v[70:73]
	ds_write_b128 v236, v[66:69] offset:16
	ds_read_b128 v[66:69], v237
	ds_read_b128 v[70:73], v237 offset:1152
	v_add_u32_e32 v140, 0x80, v206
	v_ashrrev_i32_e32 v141, 31, v140
	v_ashrrev_i32_e32 v147, 31, v146
	s_waitcnt vmcnt(15) lgkmcnt(1)
	v_pk_add_f32 v[68:69], v[136:137], v[68:69]
	v_pk_add_f32 v[66:67], v[134:135], v[66:67]
	v_ashrrev_i32_e32 v99, 31, v98
	v_cvt_pk_bf16_f32 v66, v66, v67
	v_cvt_pk_bf16_f32 v67, v68, v69
	global_store_dwordx2 v[76:77], v[66:67], off offset:256
	s_waitcnt vmcnt(15) lgkmcnt(0)
	v_pk_add_f32 v[66:67], v[132:133], v[72:73]
	v_pk_add_f32 v[68:69], v[130:131], v[70:71]
	s_nop 0
	v_cvt_pk_bf16_f32 v68, v68, v69
	v_cvt_pk_bf16_f32 v69, v66, v67
	global_store_dwordx2 v[74:75], v[68:69], off offset:256
	v_lshlrev_b64 v[66:67], 12, v[140:141]
	v_lshl_add_u64 v[66:67], v[204:205], 0, v[66:67]
	global_load_dwordx4 v[106:109], v[66:67], off
	v_lshlrev_b64 v[68:69], 12, v[142:143]
	v_lshl_add_u64 v[68:69], v[204:205], 0, v[68:69]
	global_load_dwordx4 v[110:113], v[68:69], off
	global_load_dwordx4 v[114:117], v[66:67], off offset:512
	global_load_dwordx4 v[118:121], v[68:69], off offset:512
	v_lshlrev_b64 v[66:67], 12, v[144:145]
	v_lshl_add_u64 v[66:67], v[204:205], 0, v[66:67]
	global_load_dwordx4 v[124:127], v[66:67], off
	v_lshlrev_b64 v[68:69], 12, v[146:147]
	v_lshl_add_u64 v[68:69], v[204:205], 0, v[68:69]
	global_load_dwordx4 v[128:131], v[68:69], off
	global_load_dwordx4 v[132:135], v[66:67], off offset:512
	global_load_dwordx4 v[136:139], v[68:69], off offset:512
	v_lshlrev_b64 v[66:67], 12, v[104:105]
	v_lshl_add_u64 v[66:67], v[204:205], 0, v[66:67]
	global_load_dwordx4 v[94:97], v[66:67], off
	v_lshlrev_b64 v[68:69], 12, v[102:103]
	v_lshl_add_u64 v[68:69], v[204:205], 0, v[68:69]
	global_load_dwordx4 v[90:93], v[68:69], off
	global_load_dwordx4 v[86:89], v[66:67], off offset:512
	global_load_dwordx4 v[82:85], v[68:69], off offset:512
	v_lshlrev_b64 v[66:67], 12, v[100:101]
	v_lshl_add_u64 v[66:67], v[204:205], 0, v[66:67]
	global_load_dwordx4 v[78:81], v[66:67], off
	v_lshlrev_b64 v[68:69], 12, v[98:99]
	v_lshl_add_u64 v[68:69], v[204:205], 0, v[68:69]
	global_load_dwordx4 v[74:77], v[68:69], off
	global_load_dwordx4 v[70:73], v[66:67], off offset:512
	s_nop 0
	global_load_dwordx4 v[66:69], v[68:69], off offset:512
	ds_write_b128 v236, v[62:65]
	ds_write_b128 v236, v[58:61] offset:16
	ds_read_b128 v[58:61], v237
	ds_read_b128 v[62:65], v237 offset:1152
	s_waitcnt vmcnt(15) lgkmcnt(1)
	v_pk_add_f32 v[60:61], v[108:109], v[60:61]
	v_pk_add_f32 v[58:59], v[106:107], v[58:59]
	s_waitcnt vmcnt(14) lgkmcnt(0)
	v_pk_add_f32 v[62:63], v[110:111], v[62:63]
	v_cvt_pk_bf16_f32 v58, v58, v59
	v_cvt_pk_bf16_f32 v59, v60, v61
	v_lshlrev_b64 v[60:61], 11, v[140:141]
	v_lshl_add_u64 v[60:61], s[14:15], 0, v[60:61]
	v_lshl_add_u64 v[60:61], v[60:61], 0, v[122:123]
	global_store_dwordx2 v[60:61], v[58:59], off
	v_pk_add_f32 v[58:59], v[112:113], v[64:65]
	v_cvt_pk_bf16_f32 v62, v62, v63
	v_cvt_pk_bf16_f32 v63, v58, v59
	v_lshlrev_b64 v[58:59], 11, v[142:143]
	v_lshl_add_u64 v[58:59], s[14:15], 0, v[58:59]
	v_lshl_add_u64 v[58:59], v[58:59], 0, v[122:123]
	global_store_dwordx2 v[58:59], v[62:63], off
	ds_write_b128 v236, v[54:57]
	ds_write_b128 v236, v[50:53] offset:16
	ds_read_b128 v[50:53], v237
	ds_read_b128 v[54:57], v237 offset:1152
	s_waitcnt vmcnt(15) lgkmcnt(1)
; __device__ __forceinline__ unsigned cvt_pk_bf16_v(float lo, float hi) { const f32x2c v = {lo, hi}; const bf16x2c b = __builtin_convertvector(v, bf16x2c); return __builtin_bit_cast(unsigned, b); }
;     __device__ __forceinline__ void operator()(const f32x4 (&acc)[2][2][4][2], const Unit& u_, int wr, int wc, int fr, int fq) const {
;     ...
;                     for (int t = 0; t < 2; ++t) xr[m][bj][t] = *(const f32x4*)(xp + (size_t)(rowb + ai * HALF + m * 16 + 8 * t) * 1024 + colb + bj * HALF);
;             asm volatile("" ::: "memory");
; #pragma unroll
;             for (int m = 0; m < 4; ++m)
; #pragma unroll
;                 for (int bj = 0; bj < 2; ++bj) { f32x4 o[2]; xchg_f32(xl, fr, fq, l, acc[ai][bj][m][0], acc[ai][bj][m][1], o[0], o[1]);
; #pragma unroll
;                     for (int t = 0; t < 2; ++t) { const f32x4 v = o[t] + xr[m][bj][t]; u32x2 w; w.x = cvt_pk_bf16_v(v[0], v[1]); w.y = cvt_pk_bf16_v(v[2], v[3]);
;                         *(u32x2*)(h1b + (size_t)(rowb + ai * HALF + m * 16 + 8 * t) * 1024 + colb + bj * HALF) = w; } }
;             asm volatile("" ::: "memory");
	v_pk_add_f32 v[52:53], v[116:117], v[52:53]
	v_pk_add_f32 v[50:51], v[114:115], v[50:51]
	s_nop 0
	v_cvt_pk_bf16_f32 v50, v50, v51
	v_cvt_pk_bf16_f32 v51, v52, v53
	global_store_dwordx2 v[60:61], v[50:51], off offset:256
	s_waitcnt vmcnt(15) lgkmcnt(0)
	v_pk_add_f32 v[50:51], v[120:121], v[56:57]
	v_pk_add_f32 v[52:53], v[118:119], v[54:55]
	s_nop 0
	v_cvt_pk_bf16_f32 v52, v52, v53
	v_cvt_pk_bf16_f32 v53, v50, v51
	global_store_dwordx2 v[58:59], v[52:53], off offset:256
	ds_write_b128 v236, v[46:49]
	ds_write_b128 v236, v[42:45] offset:16
	ds_read_b128 v[42:45], v237
	ds_read_b128 v[46:49], v237 offset:1152
	s_waitcnt vmcnt(15) lgkmcnt(1)
	v_pk_add_f32 v[44:45], v[126:127], v[44:45]
	v_pk_add_f32 v[42:43], v[124:125], v[42:43]
	s_waitcnt vmcnt(14) lgkmcnt(0)
	v_pk_add_f32 v[46:47], v[128:129], v[46:47]
	v_cvt_pk_bf16_f32 v42, v42, v43
	v_cvt_pk_bf16_f32 v43, v44, v45
	v_lshlrev_b64 v[44:45], 11, v[144:145]
	v_lshl_add_u64 v[44:45], s[14:15], 0, v[44:45]
	v_lshl_add_u64 v[44:45], v[44:45], 0, v[122:123]
	global_store_dwordx2 v[44:45], v[42:43], off
	v_pk_add_f32 v[42:43], v[130:131], v[48:49]
	v_cvt_pk_bf16_f32 v46, v46, v47
	v_cvt_pk_bf16_f32 v47, v42, v43
	v_lshlrev_b64 v[42:43], 11, v[146:147]
	v_lshl_add_u64 v[42:43], s[14:15], 0, v[42:43]
	v_lshl_add_u64 v[42:43], v[42:43], 0, v[122:123]
	global_store_dwordx2 v[42:43], v[46:47], off
	ds_write_b128 v236, v[38:41]
	ds_write_b128 v236, v[34:37] offset:16
	ds_read_b128 v[34:37], v237
	ds_read_b128 v[38:41], v237 offset:1152
	s_waitcnt vmcnt(15) lgkmcnt(1)
	v_pk_add_f32 v[36:37], v[134:135], v[36:37]
	v_pk_add_f32 v[34:35], v[132:133], v[34:35]
	s_nop 0
	v_cvt_pk_bf16_f32 v34, v34, v35
	v_cvt_pk_bf16_f32 v35, v36, v37
	global_store_dwordx2 v[44:45], v[34:35], off offset:256
	s_waitcnt vmcnt(15) lgkmcnt(0)
	v_pk_add_f32 v[34:35], v[138:139], v[40:41]
	v_pk_add_f32 v[36:37], v[136:137], v[38:39]
	s_nop 0
	v_cvt_pk_bf16_f32 v36, v36, v37
	v_cvt_pk_bf16_f32 v37, v34, v35
	global_store_dwordx2 v[42:43], v[36:37], off offset:256
	ds_write_b128 v236, v[30:33]
	ds_write_b128 v236, v[26:29] offset:16
	ds_read_b128 v[26:29], v237
	ds_read_b128 v[30:33], v237 offset:1152
	s_waitcnt vmcnt(15) lgkmcnt(1)
	v_pk_add_f32 v[28:29], v[96:97], v[28:29]
	v_pk_add_f32 v[26:27], v[94:95], v[26:27]
	s_waitcnt vmcnt(14) lgkmcnt(0)
	v_pk_add_f32 v[30:31], v[90:91], v[30:31]
	v_cvt_pk_bf16_f32 v26, v26, v27
	v_cvt_pk_bf16_f32 v27, v28, v29
	v_lshlrev_b64 v[28:29], 11, v[104:105]
	v_lshl_add_u64 v[28:29], s[14:15], 0, v[28:29]
	v_lshl_add_u64 v[28:29], v[28:29], 0, v[122:123]
	global_store_dwordx2 v[28:29], v[26:27], off
	v_pk_add_f32 v[26:27], v[92:93], v[32:33]
	v_cvt_pk_bf16_f32 v30, v30, v31
	v_cvt_pk_bf16_f32 v31, v26, v27
	v_lshlrev_b64 v[26:27], 11, v[102:103]
	v_lshl_add_u64 v[26:27], s[14:15], 0, v[26:27]
	v_lshl_add_u64 v[26:27], v[26:27], 0, v[122:123]
	global_store_dwordx2 v[26:27], v[30:31], off
	ds_write_b128 v236, v[22:25]
	ds_write_b128 v236, v[18:21] offset:16
	ds_read_b128 v[18:21], v237
	ds_read_b128 v[22:25], v237 offset:1152
	s_waitcnt vmcnt(15) lgkmcnt(1)
	v_pk_add_f32 v[20:21], v[88:89], v[20:21]
	v_pk_add_f32 v[18:19], v[86:87], v[18:19]
	s_nop 0
	v_cvt_pk_bf16_f32 v18, v18, v19
	v_cvt_pk_bf16_f32 v19, v20, v21
	global_store_dwordx2 v[28:29], v[18:19], off offset:256
	s_waitcnt vmcnt(15) lgkmcnt(0)
	v_pk_add_f32 v[18:19], v[84:85], v[24:25]
	v_pk_add_f32 v[20:21], v[82:83], v[22:23]
	s_nop 0
	v_cvt_pk_bf16_f32 v20, v20, v21
	v_cvt_pk_bf16_f32 v21, v18, v19
	global_store_dwordx2 v[26:27], v[20:21], off offset:256
	ds_write_b128 v236, v[14:17]
	ds_write_b128 v236, v[10:13] offset:16
	ds_read_b128 v[10:13], v237
	ds_read_b128 v[14:17], v237 offset:1152
	s_waitcnt vmcnt(15) lgkmcnt(1)
	v_pk_add_f32 v[12:13], v[80:81], v[12:13]
	v_pk_add_f32 v[10:11], v[78:79], v[10:11]
	s_waitcnt vmcnt(14) lgkmcnt(0)
	v_pk_add_f32 v[14:15], v[74:75], v[14:15]
	v_cvt_pk_bf16_f32 v10, v10, v11
	v_cvt_pk_bf16_f32 v11, v12, v13
	v_lshlrev_b64 v[12:13], 11, v[100:101]
	v_lshl_add_u64 v[12:13], s[14:15], 0, v[12:13]
	v_lshl_add_u64 v[12:13], v[12:13], 0, v[122:123]
	global_store_dwordx2 v[12:13], v[10:11], off
	v_pk_add_f32 v[10:11], v[76:77], v[16:17]
	v_cvt_pk_bf16_f32 v14, v14, v15
	v_cvt_pk_bf16_f32 v15, v10, v11
	v_lshlrev_b64 v[10:11], 11, v[98:99]
	v_lshl_add_u64 v[10:11], s[14:15], 0, v[10:11]
	v_lshl_add_u64 v[10:11], v[10:11], 0, v[122:123]
	global_store_dwordx2 v[10:11], v[14:15], off
	ds_write_b128 v236, v[6:9]
	ds_write_b128 v236, v[2:5] offset:16
	ds_read_b128 v[2:5], v237
	ds_read_b128 v[6:9], v237 offset:1152
	s_waitcnt vmcnt(15) lgkmcnt(1)
	v_pk_add_f32 v[4:5], v[72:73], v[4:5]
	v_pk_add_f32 v[2:3], v[70:71], v[2:3]
	s_nop 0
	v_cvt_pk_bf16_f32 v2, v2, v3
	v_cvt_pk_bf16_f32 v3, v4, v5
	global_store_dwordx2 v[12:13], v[2:3], off offset:256
	s_waitcnt vmcnt(15) lgkmcnt(0)
	v_pk_add_f32 v[2:3], v[68:69], v[8:9]
	v_pk_add_f32 v[4:5], v[66:67], v[6:7]
	s_nop 0
	v_cvt_pk_bf16_f32 v4, v4, v5
	v_cvt_pk_bf16_f32 v5, v2, v3
	global_store_dwordx2 v[10:11], v[4:5], off offset:256
	s_cbranch_scc1 .LBB0_831
	s_andn2_b64 vcc, exec, s[48:49]
	s_cbranch_vccnz .LBB0_830
	s_barrier
	s_branch .LBB0_830
